# v57 + SGPR-base LDS-DMA addressing also in the down and W_out K-loops (one W_out load keeps its VALU address)
# baseline (speedup 1.0000x reference)
.LBB0_243:
	s_add_u32 s22, s20, 0x100
	s_addc_u32 s23, s21, 0
	s_add_i32 s0, 0, 0x10000
	s_cmpk_eq_i32 s51, 0x54
	s_cselect_b32 s27, s7, s23
	s_cselect_b32 s26, s6, s22
	s_cselect_b32 s25, s19, s50
	s_cselect_b32 s24, s18, s49
	s_add_i32 s1, 0, 0x14000
	v_add_u32_e32 v126, s0, v237
	v_add_u32_e32 v158, s1, v237
	ds_read_b128 v[90:93], v126
	ds_read_b128 v[102:105], v126 offset:1024
	ds_read_b128 v[114:117], v126 offset:2048
	ds_read_b128 v[126:129], v126 offset:3072
	ds_read_b128 v[138:141], v158
	ds_read_b128 v[142:145], v158 offset:1024
	ds_read_b128 v[154:157], v158 offset:2048
	ds_read_b128 v[158:161], v158 offset:3072
	s_add_i32 m0, s34, 0xc000
	ds_read_b128 v[162:165], v238
	ds_read_b128 v[166:169], v238 offset:1024
	ds_read_b128 v[170:173], v238 offset:2048
	ds_read_b128 v[174:177], v238 offset:3072
	ds_read_b128 v[178:181], v238 offset:4096
	ds_read_b128 v[182:185], v238 offset:5120
	ds_read_b128 v[202:205], v238 offset:6144
	ds_read_b128 v[206:209], v238 offset:7168
	global_load_lds_dwordx4 v198, s[20:21]
	s_add_i32 m0, s34, 0xe000
	s_nop 0
	global_load_lds_dwordx4 v200, s[20:21]
	s_waitcnt vmcnt(8)
	s_waitcnt lgkmcnt(0)
	s_setprio 1
	s_barrier

	v_mfma_f32_16x16x32_bf16 v[150:153], v[90:93], v[162:165], v[150:153]
	v_mfma_f32_16x16x32_bf16 v[150:153], v[102:105], v[166:169], v[150:153]
	v_mfma_f32_16x16x32_bf16 v[146:149], v[126:129], v[166:169], v[146:149]
	v_mfma_f32_16x16x32_bf16 v[146:149], v[114:117], v[162:165], v[146:149]
	v_mfma_f32_16x16x32_bf16 v[118:121], v[114:117], v[170:173], v[118:121]
	v_mfma_f32_16x16x32_bf16 v[118:121], v[126:129], v[174:177], v[118:121]
	v_mfma_f32_16x16x32_bf16 v[122:125], v[102:105], v[174:177], v[122:125]
	v_mfma_f32_16x16x32_bf16 v[122:125], v[90:93], v[170:173], v[122:125]
	v_mfma_f32_16x16x32_bf16 v[98:101], v[90:93], v[178:181], v[98:101]
	v_mfma_f32_16x16x32_bf16 v[98:101], v[102:105], v[182:185], v[98:101]
	v_mfma_f32_16x16x32_bf16 v[94:97], v[126:129], v[182:185], v[94:97]
	v_mfma_f32_16x16x32_bf16 v[94:97], v[114:117], v[178:181], v[94:97]
	v_mfma_f32_16x16x32_bf16 v[74:77], v[114:117], v[202:205], v[74:77]
	v_mfma_f32_16x16x32_bf16 v[74:77], v[126:129], v[206:209], v[74:77]
	v_mfma_f32_16x16x32_bf16 v[78:81], v[102:105], v[206:209], v[78:81]
	v_mfma_f32_16x16x32_bf16 v[78:81], v[90:93], v[202:205], v[78:81]


	v_mfma_f32_16x16x32_bf16 v[134:137], v[138:141], v[162:165], v[134:137]
	v_mfma_f32_16x16x32_bf16 v[134:137], v[142:145], v[166:169], v[134:137]
	v_mfma_f32_16x16x32_bf16 v[130:133], v[158:161], v[166:169], v[130:133]
	v_mfma_f32_16x16x32_bf16 v[130:133], v[154:157], v[162:165], v[130:133]
	v_mfma_f32_16x16x32_bf16 v[106:109], v[154:157], v[170:173], v[106:109]
	v_mfma_f32_16x16x32_bf16 v[106:109], v[158:161], v[174:177], v[106:109]
	v_mfma_f32_16x16x32_bf16 v[110:113], v[142:145], v[174:177], v[110:113]
	v_mfma_f32_16x16x32_bf16 v[110:113], v[138:141], v[170:173], v[110:113]
	v_mfma_f32_16x16x32_bf16 v[86:89], v[138:141], v[178:181], v[86:89]
	v_mfma_f32_16x16x32_bf16 v[86:89], v[142:145], v[182:185], v[86:89]
	v_mfma_f32_16x16x32_bf16 v[82:85], v[158:161], v[182:185], v[82:85]
	v_mfma_f32_16x16x32_bf16 v[82:85], v[154:157], v[178:181], v[82:85]
	v_mfma_f32_16x16x32_bf16 v[66:69], v[154:157], v[202:205], v[66:69]
	v_mfma_f32_16x16x32_bf16 v[66:69], v[158:161], v[206:209], v[66:69]
	v_mfma_f32_16x16x32_bf16 v[70:73], v[142:145], v[206:209], v[70:73]
	v_mfma_f32_16x16x32_bf16 v[70:73], v[138:141], v[202:205], v[70:73]
	s_barrier
	s_setprio 0
	s_add_i32 s0, s0, s31
	s_mov_b32 m0, s0
	ds_read_b128 v[162:165], v238 offset:16384
	ds_read_b128 v[166:169], v238 offset:17408
	ds_read_b128 v[170:173], v238 offset:18432
	ds_read_b128 v[174:177], v238 offset:19456
	ds_read_b128 v[178:181], v238 offset:20480
	ds_read_b128 v[182:185], v238 offset:21504
	ds_read_b128 v[202:205], v238 offset:22528
	ds_read_b128 v[206:209], v238 offset:23552
	global_load_lds_dwordx4 v186, s[24:25]
	s_add_i32 m0, s0, 0x2000
	s_add_u32 s20, s24, 0x160000
	s_addc_u32 s21, s25, 0
	s_add_i32 s0, s1, s31
	global_load_lds_dwordx4 v196, s[24:25]
	s_mov_b32 m0, s0
	s_nop 0
	global_load_lds_dwordx4 v186, s[20:21]
	s_add_i32 m0, s0, 0x2000
	s_nop 0
	global_load_lds_dwordx4 v196, s[20:21]
	s_mov_b32 m0, s34
	s_nop 0
	global_load_lds_dwordx4 v192, s[26:27]
	s_mov_b32 m0, s35
	s_nop 0
	global_load_lds_dwordx4 v194, s[26:27]
	s_waitcnt vmcnt(8)
	s_waitcnt lgkmcnt(0)
	s_setprio 1
	s_barrier

	v_mfma_f32_16x16x32_bf16 v[62:65], v[90:93], v[162:165], v[62:65]
	v_mfma_f32_16x16x32_bf16 v[62:65], v[102:105], v[166:169], v[62:65]
	v_mfma_f32_16x16x32_bf16 v[58:61], v[126:129], v[166:169], v[58:61]
	v_mfma_f32_16x16x32_bf16 v[58:61], v[114:117], v[162:165], v[58:61]
	v_mfma_f32_16x16x32_bf16 v[42:45], v[114:117], v[170:173], v[42:45]
	v_mfma_f32_16x16x32_bf16 v[42:45], v[126:129], v[174:177], v[42:45]
	v_mfma_f32_16x16x32_bf16 v[46:49], v[102:105], v[174:177], v[46:49]
	v_mfma_f32_16x16x32_bf16 v[46:49], v[90:93], v[170:173], v[46:49]
	v_mfma_f32_16x16x32_bf16 v[30:33], v[90:93], v[178:181], v[30:33]
	v_mfma_f32_16x16x32_bf16 v[30:33], v[102:105], v[182:185], v[30:33]
	v_mfma_f32_16x16x32_bf16 v[26:29], v[126:129], v[182:185], v[26:29]
	v_mfma_f32_16x16x32_bf16 v[26:29], v[114:117], v[178:181], v[26:29]
	v_mfma_f32_16x16x32_bf16 v[10:13], v[114:117], v[202:205], v[10:13]
	v_mfma_f32_16x16x32_bf16 v[10:13], v[126:129], v[206:209], v[10:13]
	v_mfma_f32_16x16x32_bf16 v[14:17], v[102:105], v[206:209], v[14:17]
	v_mfma_f32_16x16x32_bf16 v[14:17], v[90:93], v[202:205], v[14:17]


	v_mfma_f32_16x16x32_bf16 v[54:57], v[138:141], v[162:165], v[54:57]
	v_mfma_f32_16x16x32_bf16 v[54:57], v[142:145], v[166:169], v[54:57]
	v_mfma_f32_16x16x32_bf16 v[50:53], v[158:161], v[166:169], v[50:53]
	v_mfma_f32_16x16x32_bf16 v[50:53], v[154:157], v[162:165], v[50:53]
	v_mfma_f32_16x16x32_bf16 v[34:37], v[154:157], v[170:173], v[34:37]
	v_mfma_f32_16x16x32_bf16 v[34:37], v[158:161], v[174:177], v[34:37]
	v_mfma_f32_16x16x32_bf16 v[38:41], v[142:145], v[174:177], v[38:41]
	v_mfma_f32_16x16x32_bf16 v[38:41], v[138:141], v[170:173], v[38:41]
	v_mfma_f32_16x16x32_bf16 v[22:25], v[138:141], v[178:181], v[22:25]
	v_mfma_f32_16x16x32_bf16 v[22:25], v[142:145], v[182:185], v[22:25]
	v_mfma_f32_16x16x32_bf16 v[18:21], v[158:161], v[182:185], v[18:21]
	v_mfma_f32_16x16x32_bf16 v[18:21], v[154:157], v[178:181], v[18:21]
	v_mfma_f32_16x16x32_bf16 v[2:5], v[154:157], v[202:205], v[2:5]
	v_mfma_f32_16x16x32_bf16 v[2:5], v[158:161], v[206:209], v[2:5]
	v_mfma_f32_16x16x32_bf16 v[6:9], v[142:145], v[206:209], v[6:9]
	v_mfma_f32_16x16x32_bf16 v[6:9], v[138:141], v[202:205], v[6:9]
	s_barrier
	s_setprio 0
	s_add_i32 s0, 0, 0x18000
	s_add_i32 s1, 0, 0x1c000
	v_add_u32_e32 v126, s0, v237
	v_add_u32_e32 v158, s1, v237
	ds_read_b128 v[90:93], v126
	ds_read_b128 v[102:105], v126 offset:1024
	ds_read_b128 v[114:117], v126 offset:2048
	ds_read_b128 v[126:129], v126 offset:3072
	ds_read_b128 v[138:141], v158
	ds_read_b128 v[142:145], v158 offset:1024
	ds_read_b128 v[154:157], v158 offset:2048
	ds_read_b128 v[158:161], v158 offset:3072
	s_add_u32 s20, s26, 0x160000
	s_addc_u32 s21, s27, 0
	s_mov_b32 m0, s36
	ds_read_b128 v[162:165], v238 offset:32768
	ds_read_b128 v[166:169], v238 offset:33792
	ds_read_b128 v[170:173], v238 offset:34816
	ds_read_b128 v[174:177], v238 offset:35840
	ds_read_b128 v[178:181], v238 offset:36864
	ds_read_b128 v[182:185], v238 offset:37888
	ds_read_b128 v[202:205], v238 offset:38912
	ds_read_b128 v[206:209], v238 offset:39936
	global_load_lds_dwordx4 v192, s[20:21]
	s_mov_b32 m0, s37
	s_nop 0
	global_load_lds_dwordx4 v194, s[20:21]
	s_waitcnt vmcnt(8)
	s_waitcnt lgkmcnt(0)
	s_setprio 1
	s_barrier

	v_mfma_f32_16x16x32_bf16 v[150:153], v[90:93], v[162:165], v[150:153]
	v_mfma_f32_16x16x32_bf16 v[150:153], v[102:105], v[166:169], v[150:153]
	v_mfma_f32_16x16x32_bf16 v[146:149], v[126:129], v[166:169], v[146:149]
	v_mfma_f32_16x16x32_bf16 v[146:149], v[114:117], v[162:165], v[146:149]
	v_mfma_f32_16x16x32_bf16 v[118:121], v[114:117], v[170:173], v[118:121]
	v_mfma_f32_16x16x32_bf16 v[118:121], v[126:129], v[174:177], v[118:121]
	v_mfma_f32_16x16x32_bf16 v[122:125], v[102:105], v[174:177], v[122:125]
	v_mfma_f32_16x16x32_bf16 v[122:125], v[90:93], v[170:173], v[122:125]
	v_mfma_f32_16x16x32_bf16 v[98:101], v[90:93], v[178:181], v[98:101]
	v_mfma_f32_16x16x32_bf16 v[98:101], v[102:105], v[182:185], v[98:101]
	v_mfma_f32_16x16x32_bf16 v[94:97], v[126:129], v[182:185], v[94:97]
	v_mfma_f32_16x16x32_bf16 v[94:97], v[114:117], v[178:181], v[94:97]
	v_mfma_f32_16x16x32_bf16 v[74:77], v[114:117], v[202:205], v[74:77]
	v_mfma_f32_16x16x32_bf16 v[74:77], v[126:129], v[206:209], v[74:77]
	v_mfma_f32_16x16x32_bf16 v[78:81], v[102:105], v[206:209], v[78:81]
	v_mfma_f32_16x16x32_bf16 v[78:81], v[90:93], v[202:205], v[78:81]


	v_mfma_f32_16x16x32_bf16 v[134:137], v[138:141], v[162:165], v[134:137]
	v_mfma_f32_16x16x32_bf16 v[134:137], v[142:145], v[166:169], v[134:137]
	v_mfma_f32_16x16x32_bf16 v[130:133], v[158:161], v[166:169], v[130:133]
	v_mfma_f32_16x16x32_bf16 v[130:133], v[154:157], v[162:165], v[130:133]
	v_mfma_f32_16x16x32_bf16 v[106:109], v[154:157], v[170:173], v[106:109]
	v_mfma_f32_16x16x32_bf16 v[106:109], v[158:161], v[174:177], v[106:109]
	v_mfma_f32_16x16x32_bf16 v[110:113], v[142:145], v[174:177], v[110:113]
	v_mfma_f32_16x16x32_bf16 v[110:113], v[138:141], v[170:173], v[110:113]
	v_mfma_f32_16x16x32_bf16 v[86:89], v[138:141], v[178:181], v[86:89]
	v_mfma_f32_16x16x32_bf16 v[86:89], v[142:145], v[182:185], v[86:89]
	v_mfma_f32_16x16x32_bf16 v[82:85], v[158:161], v[182:185], v[82:85]
	v_mfma_f32_16x16x32_bf16 v[82:85], v[154:157], v[178:181], v[82:85]
	v_mfma_f32_16x16x32_bf16 v[66:69], v[154:157], v[202:205], v[66:69]
	v_mfma_f32_16x16x32_bf16 v[66:69], v[158:161], v[206:209], v[66:69]
	v_mfma_f32_16x16x32_bf16 v[70:73], v[142:145], v[206:209], v[70:73]
	v_mfma_f32_16x16x32_bf16 v[70:73], v[138:141], v[202:205], v[70:73]
	s_barrier
	s_setprio 0
	s_add_i32 s0, s0, s31
	s_mov_b32 m0, s0
	ds_read_b128 v[162:165], v238 offset:49152
	ds_read_b128 v[166:169], v238 offset:50176
	ds_read_b128 v[170:173], v238 offset:51200
	ds_read_b128 v[174:177], v238 offset:52224
	ds_read_b128 v[178:181], v238 offset:53248
	ds_read_b128 v[182:185], v238 offset:54272
	ds_read_b128 v[202:205], v238 offset:55296
	ds_read_b128 v[206:209], v238 offset:56320
	s_add_u32 s100, s24, 0x80
	s_addc_u32 s101, s25, 0
	global_load_lds_dwordx4 v186, s[100:101]
	s_add_i32 m0, s0, 0x2000
	s_add_u32 s20, s24, 0x160080
	s_addc_u32 s21, s25, 0
	s_add_i32 s0, s1, s31
	s_add_u32 s100, s24, 0x80
	s_addc_u32 s101, s25, 0
	global_load_lds_dwordx4 v196, s[100:101]
	s_mov_b32 m0, s0
	s_nop 0
	global_load_lds_dwordx4 v186, s[20:21]
	s_add_i32 m0, s0, 0x2000
	s_nop 0
	global_load_lds_dwordx4 v196, s[20:21]
	s_mov_b32 m0, s41
	s_nop 0
	s_add_u32 s100, s26, 0x80
	s_addc_u32 s101, s27, 0
	global_load_lds_dwordx4 v192, s[100:101]
	s_mov_b32 m0, s42
	s_nop 0
	s_add_u32 s100, s26, 0x80
	s_addc_u32 s101, s27, 0
	global_load_lds_dwordx4 v194, s[100:101]
	s_waitcnt vmcnt(8)
	s_waitcnt lgkmcnt(0)
	s_setprio 1
	s_barrier

	v_mfma_f32_16x16x32_bf16 v[62:65], v[90:93], v[162:165], v[62:65]
	v_mfma_f32_16x16x32_bf16 v[62:65], v[102:105], v[166:169], v[62:65]
	v_mfma_f32_16x16x32_bf16 v[58:61], v[126:129], v[166:169], v[58:61]
	v_mfma_f32_16x16x32_bf16 v[58:61], v[114:117], v[162:165], v[58:61]
	v_mfma_f32_16x16x32_bf16 v[42:45], v[114:117], v[170:173], v[42:45]
	v_mfma_f32_16x16x32_bf16 v[42:45], v[126:129], v[174:177], v[42:45]
	v_mfma_f32_16x16x32_bf16 v[46:49], v[102:105], v[174:177], v[46:49]
	v_mfma_f32_16x16x32_bf16 v[46:49], v[90:93], v[170:173], v[46:49]
	v_mfma_f32_16x16x32_bf16 v[30:33], v[90:93], v[178:181], v[30:33]
	v_mfma_f32_16x16x32_bf16 v[30:33], v[102:105], v[182:185], v[30:33]
	v_mfma_f32_16x16x32_bf16 v[26:29], v[126:129], v[182:185], v[26:29]
	v_mfma_f32_16x16x32_bf16 v[26:29], v[114:117], v[178:181], v[26:29]
	v_mfma_f32_16x16x32_bf16 v[10:13], v[114:117], v[202:205], v[10:13]
	v_mfma_f32_16x16x32_bf16 v[10:13], v[126:129], v[206:209], v[10:13]
	v_mfma_f32_16x16x32_bf16 v[14:17], v[102:105], v[206:209], v[14:17]
	v_mfma_f32_16x16x32_bf16 v[14:17], v[90:93], v[202:205], v[14:17]


	v_mfma_f32_16x16x32_bf16 v[54:57], v[138:141], v[162:165], v[54:57]
	v_mfma_f32_16x16x32_bf16 v[54:57], v[142:145], v[166:169], v[54:57]
	v_mfma_f32_16x16x32_bf16 v[50:53], v[158:161], v[166:169], v[50:53]
	v_mfma_f32_16x16x32_bf16 v[50:53], v[154:157], v[162:165], v[50:53]
	v_mfma_f32_16x16x32_bf16 v[34:37], v[154:157], v[170:173], v[34:37]
	v_mfma_f32_16x16x32_bf16 v[34:37], v[158:161], v[174:177], v[34:37]
	v_mfma_f32_16x16x32_bf16 v[38:41], v[142:145], v[174:177], v[38:41]
	v_mfma_f32_16x16x32_bf16 v[38:41], v[138:141], v[170:173], v[38:41]
	v_mfma_f32_16x16x32_bf16 v[22:25], v[138:141], v[178:181], v[22:25]
	v_mfma_f32_16x16x32_bf16 v[22:25], v[142:145], v[182:185], v[22:25]
	v_mfma_f32_16x16x32_bf16 v[18:21], v[158:161], v[182:185], v[18:21]
	v_mfma_f32_16x16x32_bf16 v[18:21], v[154:157], v[178:181], v[18:21]
	v_mfma_f32_16x16x32_bf16 v[2:5], v[154:157], v[202:205], v[2:5]
	v_mfma_f32_16x16x32_bf16 v[2:5], v[158:161], v[206:209], v[2:5]
	v_mfma_f32_16x16x32_bf16 v[6:9], v[142:145], v[206:209], v[6:9]
	v_mfma_f32_16x16x32_bf16 v[6:9], v[138:141], v[202:205], v[6:9]
	s_barrier
	s_setprio 0
	s_add_i32 s51, s51, 2
	s_add_u32 s49, s49, 0x100
	s_addc_u32 s50, s50, 0
	s_cmpk_gt_u32 s51, 0x55
	s_mov_b64 s[20:21], s[22:23]
	s_cbranch_scc0 .LBB0_243
	s_and_b64 vcc, exec, s[16:17]
	s_cbranch_vccz .LBB0_246
	s_barrier

.LBB0_1126:
	s_add_u32 s0, s28, 0xfff80080
	s_addc_u32 s1, s29, -1
	s_add_i32 s54, 0, 0x10000
	s_cmp_eq_u32 s53, 28
	s_cselect_b32 s35, s19, s1
	s_cselect_b32 s34, s25, s0
	s_cselect_b32 s31, s17, s52
	s_cselect_b32 s30, s27, s51
	s_add_i32 s55, 0, 0x14000
	v_add_u32_e32 v126, s54, v237
	v_add_u32_e32 v158, s55, v237
	ds_read_b128 v[90:93], v126
	ds_read_b128 v[102:105], v126 offset:1024
	ds_read_b128 v[114:117], v126 offset:2048
	ds_read_b128 v[126:129], v126 offset:3072
	ds_read_b128 v[138:141], v158
	ds_read_b128 v[142:145], v158 offset:1024
	ds_read_b128 v[154:157], v158 offset:2048
	ds_read_b128 v[158:161], v158 offset:3072
	s_add_i32 m0, s40, 0xc000
	ds_read_b128 v[162:165], v238
	ds_read_b128 v[166:169], v238 offset:1024
	ds_read_b128 v[170:173], v238 offset:2048
	ds_read_b128 v[174:177], v238 offset:3072
	ds_read_b128 v[178:181], v238 offset:4096
	ds_read_b128 v[182:185], v238 offset:5120
	ds_read_b128 v[202:205], v238 offset:6144
	ds_read_b128 v[206:209], v238 offset:7168
	global_load_lds_dwordx4 v198, s[28:29]
	s_add_i32 m0, s40, 0xe000
	s_nop 0
	global_load_lds_dwordx4 v200, s[28:29]
	s_waitcnt vmcnt(8)
	s_waitcnt lgkmcnt(0)
	s_setprio 1
	s_barrier

	v_mfma_f32_16x16x32_bf16 v[150:153], v[90:93], v[162:165], v[150:153]
	v_mfma_f32_16x16x32_bf16 v[150:153], v[102:105], v[166:169], v[150:153]
	v_mfma_f32_16x16x32_bf16 v[146:149], v[126:129], v[166:169], v[146:149]
	v_mfma_f32_16x16x32_bf16 v[146:149], v[114:117], v[162:165], v[146:149]
	v_mfma_f32_16x16x32_bf16 v[118:121], v[114:117], v[170:173], v[118:121]
	v_mfma_f32_16x16x32_bf16 v[118:121], v[126:129], v[174:177], v[118:121]
	v_mfma_f32_16x16x32_bf16 v[122:125], v[102:105], v[174:177], v[122:125]
	v_mfma_f32_16x16x32_bf16 v[122:125], v[90:93], v[170:173], v[122:125]
	v_mfma_f32_16x16x32_bf16 v[98:101], v[90:93], v[178:181], v[98:101]
	v_mfma_f32_16x16x32_bf16 v[98:101], v[102:105], v[182:185], v[98:101]
	v_mfma_f32_16x16x32_bf16 v[94:97], v[126:129], v[182:185], v[94:97]
	v_mfma_f32_16x16x32_bf16 v[94:97], v[114:117], v[178:181], v[94:97]
	v_mfma_f32_16x16x32_bf16 v[74:77], v[114:117], v[202:205], v[74:77]
	v_mfma_f32_16x16x32_bf16 v[74:77], v[126:129], v[206:209], v[74:77]
	v_mfma_f32_16x16x32_bf16 v[78:81], v[102:105], v[206:209], v[78:81]
	v_mfma_f32_16x16x32_bf16 v[78:81], v[90:93], v[202:205], v[78:81]


	v_mfma_f32_16x16x32_bf16 v[134:137], v[138:141], v[162:165], v[134:137]
	v_mfma_f32_16x16x32_bf16 v[134:137], v[142:145], v[166:169], v[134:137]
	v_mfma_f32_16x16x32_bf16 v[130:133], v[158:161], v[166:169], v[130:133]
	v_mfma_f32_16x16x32_bf16 v[130:133], v[154:157], v[162:165], v[130:133]
	v_mfma_f32_16x16x32_bf16 v[106:109], v[154:157], v[170:173], v[106:109]
	v_mfma_f32_16x16x32_bf16 v[106:109], v[158:161], v[174:177], v[106:109]
	v_mfma_f32_16x16x32_bf16 v[110:113], v[142:145], v[174:177], v[110:113]
	v_mfma_f32_16x16x32_bf16 v[110:113], v[138:141], v[170:173], v[110:113]
	v_mfma_f32_16x16x32_bf16 v[86:89], v[138:141], v[178:181], v[86:89]
	v_mfma_f32_16x16x32_bf16 v[86:89], v[142:145], v[182:185], v[86:89]
	v_mfma_f32_16x16x32_bf16 v[82:85], v[158:161], v[182:185], v[82:85]
	v_mfma_f32_16x16x32_bf16 v[82:85], v[154:157], v[178:181], v[82:85]
	v_mfma_f32_16x16x32_bf16 v[66:69], v[154:157], v[202:205], v[66:69]
	v_mfma_f32_16x16x32_bf16 v[66:69], v[158:161], v[206:209], v[66:69]
	v_mfma_f32_16x16x32_bf16 v[70:73], v[142:145], v[206:209], v[70:73]
	v_mfma_f32_16x16x32_bf16 v[70:73], v[138:141], v[202:205], v[70:73]
	s_barrier
	s_setprio 0
	s_add_i32 s0, s54, s39
	s_mov_b32 m0, s0
	ds_read_b128 v[162:165], v238 offset:16384
	ds_read_b128 v[166:169], v238 offset:17408
	ds_read_b128 v[170:173], v238 offset:18432
	ds_read_b128 v[174:177], v238 offset:19456
	ds_read_b128 v[178:181], v238 offset:20480
	ds_read_b128 v[182:185], v238 offset:21504
	ds_read_b128 v[202:205], v238 offset:22528
	ds_read_b128 v[206:209], v238 offset:23552
	global_load_lds_dwordx4 v186, s[30:31]
	s_add_i32 m0, s0, 0x2000
	s_add_u32 s0, s30, 0x80000
	v_lshl_add_u64 v[210:211], s[30:31], 0, v[196:197]
	s_addc_u32 s1, s31, 0
	s_add_i32 s54, s55, s39
	global_load_lds_dwordx4 v196, s[30:31]
	s_mov_b32 m0, s54
	s_nop 0
	global_load_lds_dwordx4 v186, s[0:1]
	s_add_i32 m0, s54, 0x2000
	s_nop 0
	global_load_lds_dwordx4 v196, s[0:1]
	s_mov_b32 m0, s40
	s_nop 0
	global_load_lds_dwordx4 v192, s[34:35]
	s_mov_b32 m0, s41
	s_nop 0
	global_load_lds_dwordx4 v194, s[34:35]
	s_waitcnt vmcnt(8)
	s_waitcnt lgkmcnt(0)
	s_setprio 1
	s_barrier

	v_mfma_f32_16x16x32_bf16 v[62:65], v[90:93], v[162:165], v[62:65]
	v_mfma_f32_16x16x32_bf16 v[62:65], v[102:105], v[166:169], v[62:65]
	v_mfma_f32_16x16x32_bf16 v[58:61], v[126:129], v[166:169], v[58:61]
	v_mfma_f32_16x16x32_bf16 v[58:61], v[114:117], v[162:165], v[58:61]
	v_mfma_f32_16x16x32_bf16 v[42:45], v[114:117], v[170:173], v[42:45]
	v_mfma_f32_16x16x32_bf16 v[42:45], v[126:129], v[174:177], v[42:45]
	v_mfma_f32_16x16x32_bf16 v[46:49], v[102:105], v[174:177], v[46:49]
	v_mfma_f32_16x16x32_bf16 v[46:49], v[90:93], v[170:173], v[46:49]
	v_mfma_f32_16x16x32_bf16 v[30:33], v[90:93], v[178:181], v[30:33]
	v_mfma_f32_16x16x32_bf16 v[30:33], v[102:105], v[182:185], v[30:33]
	v_mfma_f32_16x16x32_bf16 v[26:29], v[126:129], v[182:185], v[26:29]
	v_mfma_f32_16x16x32_bf16 v[26:29], v[114:117], v[178:181], v[26:29]
	v_mfma_f32_16x16x32_bf16 v[10:13], v[114:117], v[202:205], v[10:13]
	v_mfma_f32_16x16x32_bf16 v[10:13], v[126:129], v[206:209], v[10:13]
	v_mfma_f32_16x16x32_bf16 v[14:17], v[102:105], v[206:209], v[14:17]
	v_mfma_f32_16x16x32_bf16 v[14:17], v[90:93], v[202:205], v[14:17]


	v_mfma_f32_16x16x32_bf16 v[54:57], v[138:141], v[162:165], v[54:57]
	v_mfma_f32_16x16x32_bf16 v[54:57], v[142:145], v[166:169], v[54:57]
	v_mfma_f32_16x16x32_bf16 v[50:53], v[158:161], v[166:169], v[50:53]
	v_mfma_f32_16x16x32_bf16 v[50:53], v[154:157], v[162:165], v[50:53]
	v_mfma_f32_16x16x32_bf16 v[34:37], v[154:157], v[170:173], v[34:37]
	v_mfma_f32_16x16x32_bf16 v[34:37], v[158:161], v[174:177], v[34:37]
	v_mfma_f32_16x16x32_bf16 v[38:41], v[142:145], v[174:177], v[38:41]
	v_mfma_f32_16x16x32_bf16 v[38:41], v[138:141], v[170:173], v[38:41]
	v_mfma_f32_16x16x32_bf16 v[22:25], v[138:141], v[178:181], v[22:25]
	v_mfma_f32_16x16x32_bf16 v[22:25], v[142:145], v[182:185], v[22:25]
	v_mfma_f32_16x16x32_bf16 v[18:21], v[158:161], v[182:185], v[18:21]
	v_mfma_f32_16x16x32_bf16 v[18:21], v[154:157], v[178:181], v[18:21]
	v_mfma_f32_16x16x32_bf16 v[2:5], v[154:157], v[202:205], v[2:5]
	v_mfma_f32_16x16x32_bf16 v[2:5], v[158:161], v[206:209], v[2:5]
	v_mfma_f32_16x16x32_bf16 v[6:9], v[142:145], v[206:209], v[6:9]
	v_mfma_f32_16x16x32_bf16 v[6:9], v[138:141], v[202:205], v[6:9]
	s_barrier
	s_setprio 0
	s_add_i32 s54, 0, 0x18000
	s_add_i32 s55, 0, 0x1c000
	v_add_u32_e32 v126, s54, v237
	v_add_u32_e32 v158, s55, v237
	ds_read_b128 v[90:93], v126
	ds_read_b128 v[102:105], v126 offset:1024
	ds_read_b128 v[114:117], v126 offset:2048
	ds_read_b128 v[126:129], v126 offset:3072
	ds_read_b128 v[138:141], v158
	ds_read_b128 v[142:145], v158 offset:1024
	ds_read_b128 v[154:157], v158 offset:2048
	ds_read_b128 v[158:161], v158 offset:3072
	s_add_u32 s0, s34, 0x80000
	s_addc_u32 s1, s35, 0
	s_mov_b32 m0, s42
	ds_read_b128 v[162:165], v238 offset:32768
	ds_read_b128 v[166:169], v238 offset:33792
	ds_read_b128 v[170:173], v238 offset:34816
	ds_read_b128 v[174:177], v238 offset:35840
	ds_read_b128 v[178:181], v238 offset:36864
	ds_read_b128 v[182:185], v238 offset:37888
	ds_read_b128 v[202:205], v238 offset:38912
	ds_read_b128 v[206:209], v238 offset:39936
	global_load_lds_dwordx4 v192, s[0:1]
	s_mov_b32 m0, s43
	s_nop 0
	global_load_lds_dwordx4 v194, s[0:1]
	s_waitcnt vmcnt(8)
	s_waitcnt lgkmcnt(0)
	s_setprio 1
	s_barrier

	v_mfma_f32_16x16x32_bf16 v[150:153], v[90:93], v[162:165], v[150:153]
	v_mfma_f32_16x16x32_bf16 v[150:153], v[102:105], v[166:169], v[150:153]
	v_mfma_f32_16x16x32_bf16 v[146:149], v[126:129], v[166:169], v[146:149]
	v_mfma_f32_16x16x32_bf16 v[146:149], v[114:117], v[162:165], v[146:149]
	v_mfma_f32_16x16x32_bf16 v[118:121], v[114:117], v[170:173], v[118:121]
	v_mfma_f32_16x16x32_bf16 v[118:121], v[126:129], v[174:177], v[118:121]
	v_mfma_f32_16x16x32_bf16 v[122:125], v[102:105], v[174:177], v[122:125]
	v_mfma_f32_16x16x32_bf16 v[122:125], v[90:93], v[170:173], v[122:125]
	v_mfma_f32_16x16x32_bf16 v[98:101], v[90:93], v[178:181], v[98:101]
	v_mfma_f32_16x16x32_bf16 v[98:101], v[102:105], v[182:185], v[98:101]
	v_mfma_f32_16x16x32_bf16 v[94:97], v[126:129], v[182:185], v[94:97]
	v_mfma_f32_16x16x32_bf16 v[94:97], v[114:117], v[178:181], v[94:97]
	v_mfma_f32_16x16x32_bf16 v[74:77], v[114:117], v[202:205], v[74:77]
	v_mfma_f32_16x16x32_bf16 v[74:77], v[126:129], v[206:209], v[74:77]
	v_mfma_f32_16x16x32_bf16 v[78:81], v[102:105], v[206:209], v[78:81]
	v_mfma_f32_16x16x32_bf16 v[78:81], v[90:93], v[202:205], v[78:81]


	v_mfma_f32_16x16x32_bf16 v[134:137], v[138:141], v[162:165], v[134:137]
	v_mfma_f32_16x16x32_bf16 v[134:137], v[142:145], v[166:169], v[134:137]
	v_mfma_f32_16x16x32_bf16 v[130:133], v[158:161], v[166:169], v[130:133]
	v_mfma_f32_16x16x32_bf16 v[130:133], v[154:157], v[162:165], v[130:133]
	v_mfma_f32_16x16x32_bf16 v[106:109], v[154:157], v[170:173], v[106:109]
	v_mfma_f32_16x16x32_bf16 v[106:109], v[158:161], v[174:177], v[106:109]
	v_mfma_f32_16x16x32_bf16 v[110:113], v[142:145], v[174:177], v[110:113]
	v_mfma_f32_16x16x32_bf16 v[110:113], v[138:141], v[170:173], v[110:113]
	v_mfma_f32_16x16x32_bf16 v[86:89], v[138:141], v[178:181], v[86:89]
	v_mfma_f32_16x16x32_bf16 v[86:89], v[142:145], v[182:185], v[86:89]
	v_mfma_f32_16x16x32_bf16 v[82:85], v[158:161], v[182:185], v[82:85]
	v_mfma_f32_16x16x32_bf16 v[82:85], v[154:157], v[178:181], v[82:85]
	v_mfma_f32_16x16x32_bf16 v[66:69], v[154:157], v[202:205], v[66:69]
	v_mfma_f32_16x16x32_bf16 v[66:69], v[158:161], v[206:209], v[66:69]
	v_mfma_f32_16x16x32_bf16 v[70:73], v[142:145], v[206:209], v[70:73]
	v_mfma_f32_16x16x32_bf16 v[70:73], v[138:141], v[202:205], v[70:73]
	s_barrier
	s_setprio 0
	s_add_i32 s0, s54, s39
	s_mov_b32 m0, s0
	ds_read_b128 v[162:165], v238 offset:49152
	ds_read_b128 v[166:169], v238 offset:50176
	ds_read_b128 v[170:173], v238 offset:51200
	ds_read_b128 v[174:177], v238 offset:52224
	ds_read_b128 v[178:181], v238 offset:53248
	ds_read_b128 v[182:185], v238 offset:54272
	ds_read_b128 v[202:205], v238 offset:55296
	ds_read_b128 v[206:209], v238 offset:56320
	s_add_u32 s100, s30, 0x80
	s_addc_u32 s101, s31, 0
	global_load_lds_dwordx4 v186, s[100:101]
	s_add_i32 m0, s0, 0x2000
	s_add_u32 s0, s30, 0x80080
	v_lshl_add_u64 v[188:189], v[210:211], 0, s[84:85]
	s_addc_u32 s1, s31, 0
	s_add_i32 s30, s55, s39
	global_load_lds_dwordx4 v[188:189], off
	s_mov_b32 m0, s30
	s_nop 0
	global_load_lds_dwordx4 v186, s[0:1]
	s_add_i32 m0, s30, 0x2000
	s_nop 0
	global_load_lds_dwordx4 v196, s[0:1]
	s_mov_b32 m0, s47
	s_nop 0
	s_add_u32 s100, s34, 0x80
	s_addc_u32 s101, s35, 0
	global_load_lds_dwordx4 v192, s[100:101]
	s_mov_b32 m0, s48
	s_nop 0
	s_add_u32 s100, s34, 0x80
	s_addc_u32 s101, s35, 0
	global_load_lds_dwordx4 v194, s[100:101]
	s_waitcnt vmcnt(8)
	s_waitcnt lgkmcnt(0)
	s_setprio 1
	s_barrier

	v_mfma_f32_16x16x32_bf16 v[62:65], v[90:93], v[162:165], v[62:65]
	v_mfma_f32_16x16x32_bf16 v[62:65], v[102:105], v[166:169], v[62:65]
	v_mfma_f32_16x16x32_bf16 v[58:61], v[126:129], v[166:169], v[58:61]
	v_mfma_f32_16x16x32_bf16 v[58:61], v[114:117], v[162:165], v[58:61]
	v_mfma_f32_16x16x32_bf16 v[42:45], v[114:117], v[170:173], v[42:45]
	v_mfma_f32_16x16x32_bf16 v[42:45], v[126:129], v[174:177], v[42:45]
	v_mfma_f32_16x16x32_bf16 v[46:49], v[102:105], v[174:177], v[46:49]
	v_mfma_f32_16x16x32_bf16 v[46:49], v[90:93], v[170:173], v[46:49]
	v_mfma_f32_16x16x32_bf16 v[30:33], v[90:93], v[178:181], v[30:33]
	v_mfma_f32_16x16x32_bf16 v[30:33], v[102:105], v[182:185], v[30:33]
	v_mfma_f32_16x16x32_bf16 v[26:29], v[126:129], v[182:185], v[26:29]
	v_mfma_f32_16x16x32_bf16 v[26:29], v[114:117], v[178:181], v[26:29]
	v_mfma_f32_16x16x32_bf16 v[10:13], v[114:117], v[202:205], v[10:13]
	v_mfma_f32_16x16x32_bf16 v[10:13], v[126:129], v[206:209], v[10:13]
	v_mfma_f32_16x16x32_bf16 v[14:17], v[102:105], v[206:209], v[14:17]
	v_mfma_f32_16x16x32_bf16 v[14:17], v[90:93], v[202:205], v[14:17]


	v_mfma_f32_16x16x32_bf16 v[54:57], v[138:141], v[162:165], v[54:57]
	v_mfma_f32_16x16x32_bf16 v[54:57], v[142:145], v[166:169], v[54:57]
	v_mfma_f32_16x16x32_bf16 v[50:53], v[158:161], v[166:169], v[50:53]
	v_mfma_f32_16x16x32_bf16 v[50:53], v[154:157], v[162:165], v[50:53]
	v_mfma_f32_16x16x32_bf16 v[34:37], v[154:157], v[170:173], v[34:37]
	v_mfma_f32_16x16x32_bf16 v[34:37], v[158:161], v[174:177], v[34:37]
	v_mfma_f32_16x16x32_bf16 v[38:41], v[142:145], v[174:177], v[38:41]
	v_mfma_f32_16x16x32_bf16 v[38:41], v[138:141], v[170:173], v[38:41]
	v_mfma_f32_16x16x32_bf16 v[22:25], v[138:141], v[178:181], v[22:25]
	v_mfma_f32_16x16x32_bf16 v[22:25], v[142:145], v[182:185], v[22:25]
	v_mfma_f32_16x16x32_bf16 v[18:21], v[158:161], v[182:185], v[18:21]
	v_mfma_f32_16x16x32_bf16 v[18:21], v[154:157], v[178:181], v[18:21]
	v_mfma_f32_16x16x32_bf16 v[2:5], v[154:157], v[202:205], v[2:5]
	v_mfma_f32_16x16x32_bf16 v[2:5], v[158:161], v[206:209], v[2:5]
	v_mfma_f32_16x16x32_bf16 v[6:9], v[142:145], v[206:209], v[6:9]
	v_mfma_f32_16x16x32_bf16 v[6:9], v[138:141], v[202:205], v[6:9]
	s_barrier
	s_setprio 0
	s_add_i32 s53, s53, 2
	s_add_u32 s28, s28, 0x100
	s_addc_u32 s29, s29, 0
	s_add_u32 s51, s51, 0x100
	s_addc_u32 s52, s52, 0
	s_cmp_gt_u32 s53, 29
	s_cbranch_scc0 .LBB0_1126
	s_and_b64 vcc, exec, s[14:15]
	s_cbranch_vccz .LBB0_1129
	s_barrier
